# pass1 decayed keys: batched d16 loads, interleaved math, paired bf16 packs; grid-barrier waits poll the TOP counter
# speedup vs baseline: 1.0176x; 1.0041x over previous
.LBB0_208:
	s_and_saveexec_b64 s[2:3], s[60:61]
	s_cbranch_execz .LBB0_223
	v_readlane_b32 s4, v252, 28
	s_waitcnt vmcnt(0)
	s_nop 0
	v_mov_b32_e32 v0, s4
	v_add_u32_e32 v0, -8, v0
	ds_read2_b32 v[0:1], v0 offset1:2
	s_waitcnt lgkmcnt(0)
	v_mad_u32_u24 v0, v0, v1, v0
	global_load_dword v1, v16, s[56:57] offset:-256 sc1
	s_waitcnt vmcnt(0)
	v_cmp_ge_u32_e32 vcc, v1, v0
	s_cbranch_vccnz .LBB0_222
	s_mov_b32 s7, 1
	s_branch .LBB0_212

.LBB0_214:
	global_load_dword v1, v16, s[56:57] offset:-256 sc1
	s_add_i32 s7, s7, 1
	s_mov_b64 s[18:19], -1
	s_waitcnt vmcnt(0)
	v_cmp_ge_u32_e64 s[4:5], v1, v0
	s_branch .LBB0_211

.LBB0_287:
	s_cmp_gt_u32 s94, 4
	s_cselect_b64 s[26:27], -1, 0
	s_cmp_lt_u32 s94, 5
	s_cbranch_scc1 .LBB0_304
	s_and_saveexec_b64 s[0:1], s[60:61]
	s_cbranch_execz .LBB0_303
	v_readlane_b32 s2, v252, 28
	s_waitcnt vmcnt(0)
	s_nop 0
	v_mov_b32_e32 v0, s2
	v_add_u32_e32 v0, -8, v0
	ds_read2_b32 v[0:1], v0 offset1:2
	s_waitcnt lgkmcnt(0)
	v_mad_u32_u24 v0, v0, v1, v0
	global_load_dword v1, v16, s[56:57] offset:-256 sc1
	s_waitcnt vmcnt(0)
	v_cmp_ge_u32_e32 vcc, v1, v0
	s_cbranch_vccnz .LBB0_302
	s_mov_b32 s7, 1
	s_branch .LBB0_292

.LBB0_294:
	global_load_dword v1, v16, s[56:57] offset:-256 sc1
	s_add_i32 s7, s7, 1
	s_mov_b64 s[4:5], -1
	s_waitcnt vmcnt(0)
	v_cmp_ge_u32_e64 s[2:3], v1, v0
	s_branch .LBB0_291

.LBB0_1116:
	s_and_b64 vcc, exec, s[70:71]
	s_cbranch_vccnz .LBB0_1145
	s_and_saveexec_b64 s[0:1], s[60:61]
	s_cbranch_execz .LBB0_1144
	v_readlane_b32 s2, v252, 28
	s_nop 1
	v_mov_b32_e32 v0, s2
	v_add_u32_e32 v0, -8, v0
	ds_read2_b32 v[0:1], v0 offset1:2
	s_waitcnt lgkmcnt(0)
	v_mad_u32_u24 v0, v0, v1, v0
	global_load_dword v1, v16, s[56:57] offset:-256 sc1
	s_waitcnt vmcnt(0)
	v_cmp_ge_u32_e32 vcc, v1, v0
	s_cbranch_vccnz .LBB0_1143
	s_mov_b32 s8, 1
	s_branch .LBB0_1121

.LBB0_1123:
	global_load_dword v1, v16, s[56:57] offset:-256 sc1
	s_add_i32 s8, s8, 1
	s_mov_b64 s[4:5], -1
	s_waitcnt vmcnt(0)
	v_cmp_ge_u32_e64 s[2:3], v1, v0
	s_branch .LBB0_1120

.LBB0_1150:
	s_ashr_i32 s0, s2, 6
	v_mov_b32_e32 v180, 0
	v_mov_b32_e32 v181, 0
	v_mov_b32_e32 v182, 0
	v_mov_b32_e32 v183, 0
	v_mov_b32_e32 v184, 0
	v_mov_b32_e32 v185, 0
	v_mov_b32_e32 v186, 0
	v_mov_b32_e32 v187, 0
	s_ashr_i32 s1, s0, 31
	s_lshl_b32 s3, s2, 8
	s_lshl_b64 s[0:1], s[0:1], 12
	s_and_b32 s3, s3, 0xf00
	s_or_b32 s4, s0, s3
	s_mov_b32 s5, s1
	v_lshl_add_u64 v[8:9], s[4:5], 0, v[54:55]
	v_mov_b64_e32 v[10:11], s[52:53]
	s_movk_i32 s6, 0x1600
	v_mad_u64_u32 v[10:11], s[4:5], v8, s6, v[10:11]
	s_lshl_b32 s3, s2, 4
	v_mad_i32_i24 v11, v9, s6, v11
	s_and_b32 s54, s3, 0x300
	v_lshl_add_u64 v[8:9], v[10:11], 0, s[54:55]
	v_mov_b32_e32 v61, v16
	v_lshl_add_u64 v[8:9], v[8:9], 0, v[60:61]
	global_load_dwordx4 v[42:45], v[8:9], off offset:2560
	global_load_dwordx4 v[46:49], v[8:9], off offset:3584
	s_lshl_b32 s4, s8, 1
	s_and_b32 s4, s4, 0x300
	v_mov_b32_e32 v8, s4
	v_readfirstlane_b32 s4, v17
	s_ashr_i32 s5, s4, 6
	s_lshl_b32 s4, s5, 4
	v_or_b32_e32 v10, s4, v64
	s_and_b32 s3, s9, 0xf00
	v_lshlrev_b32_e32 v12, 1, v10
	v_or_b32_e32 v10, s4, v56
	v_lshlrev_b32_e32 v74, 1, v10
	v_or_b32_e32 v10, s4, v67
	s_or_b32 s0, s0, s3
	v_mov_b32_e32 v9, v16
	v_lshlrev_b32_e32 v13, 1, v10
	v_lshl_add_u64 v[10:11], s[0:1], 0, v[54:55]
	v_mad_u64_u32 v[8:9], s[0:1], v10, s6, v[8:9]
	v_mad_i32_i24 v9, v11, s6, v9
	v_mov_b32_e32 v61, 0
	v_add_u32_e32 v76, 0, v74
	v_lshl_add_u64 v[62:63], v[58:59], 0, v[8:9]
	s_mov_b64 s[6:7], 0
	v_add_u32_e32 v78, v65, v12
	v_add_u32_e32 v73, v66, v13
	v_mov_b32_e32 v8, 0
	v_mov_b32_e32 v9, v61
	v_mov_b32_e32 v10, v61
	v_mov_b32_e32 v11, v61
	v_mov_b32_e32 v12, 0
	v_mov_b32_e32 v13, v61
	v_mov_b32_e32 v14, v61
	v_mov_b32_e32 v15, v61
	v_mov_b32_e32 v18, 0
	v_mov_b32_e32 v19, v61
	v_mov_b32_e32 v20, v61
	v_mov_b32_e32 v21, v61
	v_mov_b32_e32 v22, 0
	v_mov_b32_e32 v23, v61
	v_mov_b32_e32 v24, v61
	v_mov_b32_e32 v25, v61
	v_mov_b32_e32 v26, 0
	v_mov_b32_e32 v27, v61
	v_mov_b32_e32 v28, v61
	v_mov_b32_e32 v29, v61
	v_mov_b32_e32 v30, 0
	v_mov_b32_e32 v31, v61
	v_mov_b32_e32 v32, v61
	v_mov_b32_e32 v33, v61
	v_mov_b32_e32 v34, 0
	v_mov_b32_e32 v35, v61
	v_mov_b32_e32 v36, v61
	v_mov_b32_e32 v37, v61
	v_mov_b32_e32 v38, 0
	v_mov_b32_e32 v39, v61
	v_mov_b32_e32 v40, v61
	v_mov_b32_e32 v41, v61
	v_add_u32_e32 v77, v76, v69
	s_branch .LBB0_1152

.LBB0_1152:
	s_waitcnt vmcnt(1)
	ds_write_b128 v70, v[42:45] offset:17408
	s_waitcnt vmcnt(0)
	ds_write_b128 v70, v[46:49] offset:37888
	v_lshl_add_u64 v[42:43], v[62:63], 0, s[6:7]
	s_mov_b32 s0, 0x6b2c000
	v_add_co_u32_e64 v46, s[0:1], s0, v42
	v_and_or_b32 v50, v221, 64, v56
	s_nop 0
	v_addc_co_u32_e64 v47, s[0:1], 0, v43, s[0:1]
	global_load_dwordx4 v[42:45], v[46:47], off offset:2560
	s_nop 0
	global_load_dwordx4 v[46:49], v[46:47], off offset:3584
	s_waitcnt lgkmcnt(0)
	s_barrier
	ds_read_b64_tr_b16 v[80:81], v78 offset:17408
	ds_read_b64_tr_b16 v[82:83], v78 offset:18688
	ds_read_u16_d16_hi v180, v77 offset:17408
	ds_read_u16_d16_hi v181, v77 offset:17728
	ds_read_u16_d16_hi v182, v77 offset:18048
	ds_read_u16_d16_hi v183, v77 offset:18368
	ds_read_u16_d16_hi v184, v77 offset:22528
	ds_read_u16_d16_hi v185, v77 offset:22848
	ds_read_u16_d16_hi v186, v77 offset:23168
	ds_read_u16_d16_hi v187, v77 offset:23488
	s_waitcnt lgkmcnt(8)
	v_mfma_f32_16x16x32_bf16 v[84:87], v[0:3], v[80:83], 0
	v_lshlrev_b32_e32 v79, 2, v50
	v_mfma_f32_16x16x32_bf16 v[80:83], v[4:7], v[80:83], 0
	s_nop 5
	ds_bpermute_b32 v50, v79, v87 offset:192
	s_waitcnt lgkmcnt(0)
	v_exp_f32_e32 v188, v180
	v_exp_f32_e32 v189, v181
	v_exp_f32_e32 v190, v182
	v_exp_f32_e32 v191, v183
	v_exp_f32_e32 v192, v184
	v_exp_f32_e32 v193, v185
	v_exp_f32_e32 v194, v186
	v_exp_f32_e32 v195, v187
	v_sub_f32_e32 v196, v50, v80
	v_sub_f32_e32 v197, v50, v81
	v_sub_f32_e32 v198, v50, v82
	v_sub_f32_e32 v199, v50, v83
	v_sub_f32_e32 v200, v50, v84
	v_sub_f32_e32 v201, v50, v85
	v_sub_f32_e32 v202, v50, v86
	v_sub_f32_e32 v203, v50, v87
	v_exp_f32_e32 v196, v196
	v_exp_f32_e32 v197, v197
	v_exp_f32_e32 v198, v198
	v_exp_f32_e32 v199, v199
	v_exp_f32_e32 v200, v200
	v_exp_f32_e32 v201, v201
	v_exp_f32_e32 v202, v202
	v_exp_f32_e32 v203, v203
	v_sub_f32_e32 v188, 1.0, v188
	v_sub_f32_e32 v189, 1.0, v189
	v_sub_f32_e32 v190, 1.0, v190
	v_sub_f32_e32 v191, 1.0, v191
	v_sub_f32_e32 v192, 1.0, v192
	v_sub_f32_e32 v193, 1.0, v193
	v_sub_f32_e32 v194, 1.0, v194
	v_sub_f32_e32 v195, 1.0, v195
	v_mul_f32_e32 v196, v196, v188
	v_mul_f32_e32 v197, v197, v189
	v_mul_f32_e32 v198, v198, v190
	v_mul_f32_e32 v199, v199, v191
	v_mul_f32_e32 v200, v200, v192
	v_mul_f32_e32 v201, v201, v193
	v_mul_f32_e32 v202, v202, v194
	v_mul_f32_e32 v203, v203, v195
	v_cvt_pk_bf16_f32 v204, v196, v197
	v_cvt_pk_bf16_f32 v205, v198, v199
	v_cvt_pk_bf16_f32 v206, v200, v201
	v_cvt_pk_bf16_f32 v207, v202, v203
	ds_write_b16 v77, v204 offset:27648
	ds_write_b16_d16_hi v77, v204 offset:27968
	ds_write_b16 v77, v205 offset:28288
	ds_write_b16_d16_hi v77, v205 offset:28608
	ds_write_b16 v77, v206 offset:32768
	ds_write_b16_d16_hi v77, v206 offset:33088
	ds_write_b16 v77, v207 offset:33408
	ds_write_b16_d16_hi v77, v207 offset:33728
	s_and_saveexec_b64 s[0:1], vcc
	s_cbranch_execz .LBB0_1151
	v_exp_f32_e32 v51, v50
	v_add_u32_e32 v52, v76, v74
	ds_write_b32 v52, v51 offset:56832
	s_branch .LBB0_1151
.LBB0_1154:
	s_waitcnt vmcnt(1)
	ds_write_b128 v70, v[42:45] offset:17408
	s_waitcnt vmcnt(0)
	ds_write_b128 v70, v[46:49] offset:37888
	s_waitcnt lgkmcnt(0)
	s_barrier
	ds_read_b64_tr_b16 v[42:43], v78 offset:17408
	ds_read_b64_tr_b16 v[44:45], v78 offset:18688
	ds_read_u16_d16_hi v180, v77 offset:17408
	ds_read_u16_d16_hi v181, v77 offset:17728
	ds_read_u16_d16_hi v182, v77 offset:18048
	ds_read_u16_d16_hi v183, v77 offset:18368
	ds_read_u16_d16_hi v184, v77 offset:22528
	ds_read_u16_d16_hi v185, v77 offset:22848
	ds_read_u16_d16_hi v186, v77 offset:23168
	ds_read_u16_d16_hi v187, v77 offset:23488
	s_waitcnt lgkmcnt(8)
	v_mfma_f32_16x16x32_bf16 v[48:51], v[0:3], v[42:45], 0
	v_or_b32_e32 v46, 0xc0, v79
	v_mfma_f32_16x16x32_bf16 v[42:45], v[4:7], v[42:45], 0
	s_nop 5
	ds_bpermute_b32 v46, v46, v51
	s_waitcnt lgkmcnt(0)
	v_exp_f32_e32 v188, v180
	v_exp_f32_e32 v189, v181
	v_exp_f32_e32 v190, v182
	v_exp_f32_e32 v191, v183
	v_exp_f32_e32 v192, v184
	v_exp_f32_e32 v193, v185
	v_exp_f32_e32 v194, v186
	v_exp_f32_e32 v195, v187
	v_sub_f32_e32 v196, v46, v42
	v_sub_f32_e32 v197, v46, v43
	v_sub_f32_e32 v198, v46, v44
	v_sub_f32_e32 v199, v46, v45
	v_sub_f32_e32 v200, v46, v48
	v_sub_f32_e32 v201, v46, v49
	v_sub_f32_e32 v202, v46, v50
	v_sub_f32_e32 v203, v46, v51
	v_exp_f32_e32 v196, v196
	v_exp_f32_e32 v197, v197
	v_exp_f32_e32 v198, v198
	v_exp_f32_e32 v199, v199
	v_exp_f32_e32 v200, v200
	v_exp_f32_e32 v201, v201
	v_exp_f32_e32 v202, v202
	v_exp_f32_e32 v203, v203
	v_sub_f32_e32 v188, 1.0, v188
	v_sub_f32_e32 v189, 1.0, v189
	v_sub_f32_e32 v190, 1.0, v190
	v_sub_f32_e32 v191, 1.0, v191
	v_sub_f32_e32 v192, 1.0, v192
	v_sub_f32_e32 v193, 1.0, v193
	v_sub_f32_e32 v194, 1.0, v194
	v_sub_f32_e32 v195, 1.0, v195
	v_mul_f32_e32 v196, v196, v188
	v_mul_f32_e32 v197, v197, v189
	v_mul_f32_e32 v198, v198, v190
	v_mul_f32_e32 v199, v199, v191
	v_mul_f32_e32 v200, v200, v192
	v_mul_f32_e32 v201, v201, v193
	v_mul_f32_e32 v202, v202, v194
	v_mul_f32_e32 v203, v203, v195
	v_cvt_pk_bf16_f32 v204, v196, v197
	v_cvt_pk_bf16_f32 v205, v198, v199
	v_cvt_pk_bf16_f32 v206, v200, v201
	v_cvt_pk_bf16_f32 v207, v202, v203
	ds_write_b16 v77, v204 offset:27648
	ds_write_b16_d16_hi v77, v204 offset:27968
	ds_write_b16 v77, v205 offset:28288
	ds_write_b16_d16_hi v77, v205 offset:28608
	ds_write_b16 v77, v206 offset:32768
	ds_write_b16_d16_hi v77, v206 offset:33088
	ds_write_b16 v77, v207 offset:33408
	ds_write_b16_d16_hi v77, v207 offset:33728
	s_and_saveexec_b64 s[0:1], vcc
	s_cbranch_execz .LBB0_1156
	v_exp_f32_e32 v42, v46
	v_add_u32_e32 v43, v76, v74
	ds_write_b32 v43, v42 offset:56832

.LBB0_1265:
	s_andn2_b64 vcc, exec, s[18:19]
	s_mov_b64 s[0:1], -1
	s_cbranch_vccnz .LBB0_1186
	s_and_saveexec_b64 s[0:1], s[60:61]
	s_cbranch_execz .LBB0_1281
	v_readlane_b32 s2, v252, 28
	s_waitcnt vmcnt(9)
	s_nop 0
	v_mov_b32_e32 v0, s2
	v_add_u32_e32 v0, -8, v0
	ds_read2_b32 v[0:1], v0 offset1:2
	s_waitcnt lgkmcnt(0)
	v_mad_u32_u24 v0, v0, v1, v0
	global_load_dword v1, v16, s[56:57] offset:-256 sc1
	s_waitcnt vmcnt(0)
	v_cmp_ge_u32_e32 vcc, v1, v0
	s_cbranch_vccnz .LBB0_1280
	s_mov_b32 s8, 1
	s_branch .LBB0_1270

.LBB0_1308:
	s_and_saveexec_b64 s[0:1], s[60:61]
	v_readlane_b32 s50, v252, 47
	v_readlane_b32 s62, v253, 5
	v_readlane_b32 s64, v253, 7
	v_readlane_b32 s42, v253, 19
	v_readlane_b32 s45, v252, 44
	v_readlane_b32 s46, v252, 45
	v_readlane_b32 s47, v252, 46
	v_readlane_b32 s51, v252, 48
	v_readlane_b32 s63, v253, 6
	v_readlane_b32 s65, v253, 8
	s_cbranch_execz .LBB0_1323
	v_readlane_b32 s2, v252, 28
	s_waitcnt vmcnt(9)
	s_nop 0
	v_mov_b32_e32 v0, s2
	v_add_u32_e32 v0, -8, v0
	ds_read2_b32 v[0:1], v0 offset1:2
	s_waitcnt lgkmcnt(0)
	v_mad_u32_u24 v0, v0, v1, v0
	global_load_dword v1, v16, s[56:57] offset:-256 sc1
	s_waitcnt vmcnt(0)
	v_cmp_ge_u32_e32 vcc, v1, v0
	s_cbranch_vccnz .LBB0_1322
	s_mov_b32 s8, 1
	s_branch .LBB0_1312

.LBB0_1499:
	v_readlane_b32 s2, v252, 28
	s_nop 1
	v_mov_b32_e32 v0, s2
	v_add_u32_e32 v0, -8, v0
	ds_read2_b32 v[0:1], v0 offset1:2
	s_waitcnt lgkmcnt(0)
	v_mad_u32_u24 v0, v0, v1, v0
	global_load_dword v1, v16, s[56:57] offset:-256 sc1
	s_waitcnt vmcnt(0)
	v_cmp_ge_u32_e32 vcc, v1, v0
	s_cbranch_vccz .LBB0_1500
	s_getpc_b64 s[98:99]
